# scan producers: token-step math list-scheduled (temporaries renamed, four tokens' chains interleaved)
# baseline (speedup 1.0000x reference)
; __device__ __forceinline__ float bf2f(unsigned v) { return __uint_as_float(v << 16); }
; __device__ __forceinline__ bf16_t f2bf(float f) { return (bf16_t)(pkbf(f, 0.f) & 0xffffu); }
; __device__ __forceinline__ void scan_unit_mfma(const TI ti, CArgs& a, int l, int u, bool ctx_out, unsigned char* ldsg) {
;     ...
;                 for (int i4 = 0; i4 < 4; ++i4) {
;                     const int t = 4 * (k & 3) + i4; const int tok = SC2_TOK(Tn_, cc_, t);
;                     Lsum = (t == 0) ? 0.f : Lsum; ePprev = (t == 0) ? 1.f : ePprev;
;                     const float mp_ = tok > 0 ? 0.5f : 0.f, mn_ = tok < Tn_ - 1 ? 0.5f : 0.f;
;                     const float xr = bf2f(cur[i4][1]), xk = bf2f(cur[i4][4]), xv = bf2f(cur[i4][7]);
;                     const float zr = xr + mur * ((mp_ * bf2f(cur[i4][0]) + mn_ * bf2f(cur[i4][2])) - xr);
;                     const float zk = xk + muk * ((mp_ * bf2f(cur[i4][3]) + mn_ * bf2f(cur[i4][5])) - xk);
;                     const float zv = xv + muv * ((mp_ * bf2f(cur[i4][6]) + mn_ * bf2f(cur[i4][8])) - xv);
;                     const float kkv = zk * kkg; const float ssq = wave_sum(kkv * kkv); const float kkn = kkv * rsqrtf(fmaxf(ssq, 1e-24f));
;                     const float ad = bf2f(cur[i4][10]); const float kd = zk * (1.f + (ad - 1.f) * kag);
;                     Lsum += bf2f(cur[i4][9]);
;                     const float eP = __expf(Lsum), eI = __expf(-Lsum);
;                     AR[t * 72 + lane] = f2bf(-kkn * ePprev); AR[(16 + t) * 72 + lane] = f2bf(zr * eP);
;                     const bf16_t bt = f2bf(kkn * ad * eI), kt = f2bf(kd * eI);
;                     BK[t * 72 + lane] = bt; BK[(16 + t) * 72 + lane] = kt;
;                     BKT[lane * 40 + t] = bt; BKT[lane * 40 + 16 + t] = kt;
;                     VTT[lane * 24 + t] = f2bf(zv);
;                     PC[lane] = eP;
;                     ePprev = eP;
;                 }
.LBB0_306:
	s_mulk_i32 s1, 0xab
	s_bfe_u32 s1, s1, 0x6000a
	s_mul_i32 s1, s1, 6
	s_add_i32 s1, s1, s27
	s_lshl_b32 s4, s1, 4
	s_add_i32 s5, s4, 0xffffff00
	s_cmp_lt_i32 s1, 16
	s_mul_i32 s6, s3, 24
	s_cselect_b32 s1, 0x100, s90
	s_cselect_b32 s36, s4, s5
	s_mul_i32 s7, s3, 0xfffff280
	s_mul_i32 s33, s3, 0xffffffd0
	s_mulk_i32 s3, 0xffe8
	s_add_i32 s4, s1, -1
	s_add_i32 s5, s36, s94
	s_sub_i32 s1, s1, s36
	s_add_i32 s6, s93, s6
	s_add_i32 s5, s5, s3
	s_add_i32 s6, s6, s1
	s_add_i32 s99, s5, -3
	s_add_i32 s98, s6, 3
	s_and_b64 s[66:67], s[60:61], exec
	s_cselect_b32 s98, s99, s98
	s_cmp_eq_u32 s10, 0
	s_cselect_b64 s[66:67], -1, 0
	v_cndmask_b32_e64 v73, v73, 0, s[66:67]
	v_cndmask_b32_e64 v74, v74, 1.0, s[66:67]
	s_cmp_gt_i32 s98, 0
	s_cselect_b64 s[66:67], -1, 0
	v_cndmask_b32_e64 v119, 0, 0.5, s[66:67]
	s_cmp_lt_i32 s98, s4
	s_cselect_b64 s[66:67], -1, 0
	v_cndmask_b32_e64 v120, 0, 0.5, s[66:67]
	s_add_i32 s98, s5, -2
	s_add_i32 s99, s6, 2
	s_and_b64 s[66:67], s[60:61], exec
	s_cselect_b32 s98, s98, s99
	s_cmp_gt_i32 s98, 0
	v_lshlrev_b32_e32 v67, 16, v67
	s_cselect_b64 s[66:67], -1, 0
	v_cndmask_b32_e64 v121, 0, 0.5, s[66:67]
	v_lshlrev_b32_e32 v66, 16, v66
	v_mul_f32_e32 v67, v120, v67
	s_cmp_lt_i32 s98, s4
	s_cselect_b64 s[66:67], -1, 0
	v_lshlrev_b32_e32 v70, 16, v70
	v_fmac_f32_e32 v67, v119, v66
	v_cndmask_b32_e64 v122, 0, 0.5, s[66:67]
	s_add_i32 s98, s5, -1
	s_add_i32 s99, s6, 1
	v_sub_f32_e32 v123, v67, v70
	s_and_b64 s[66:67], s[60:61], exec
	s_cselect_b32 s98, s98, s99
	v_fmac_f32_e32 v70, v18, v123
	v_lshlrev_b32_e32 v47, 16, v47
	s_cmp_gt_i32 s98, 0
	s_cselect_b64 s[66:67], -1, 0
	v_mul_f32_e32 v124, v20, v70
	v_lshlrev_b32_e32 v44, 16, v44
	v_mul_f32_e32 v47, v122, v47
	v_cndmask_b32_e64 v125, 0, 0.5, s[66:67]
	s_cmp_lt_i32 s98, s4
	v_mul_f32_e32 v126, v124, v124
	v_lshlrev_b32_e32 v61, 16, v61
	v_fmac_f32_e32 v47, v121, v44
	s_cselect_b64 s[66:67], -1, 0
	v_cndmask_b32_e64 v127, 0, 0.5, s[66:67]
	v_mov_b32_dpp v126, v126 quad_perm:[1,0,3,2] row_mask:0xf bank_mask:0xf bound_ctrl:1
	v_sub_f32_e32 v128, v47, v61
	v_lshlrev_b32_e32 v129, 16, v45
	s_and_b64 s[66:67], s[60:61], exec
	v_fmac_f32_e32 v61, v18, v128
	v_lshlrev_b32_e32 v25, 16, v25
	v_mul_f32_e32 v129, v127, v129
	s_cselect_b32 s98, s5, s6
	v_fmac_f32_e32 v126, v124, v124
	s_cmp_gt_i32 s98, 0
	v_mul_f32_e32 v130, v20, v61
	v_lshlrev_b32_e32 v131, 16, v57
	v_fmac_f32_e32 v129, v125, v25
	s_cselect_b64 s[84:85], -1, 0
	v_add_f32_dpp v126, v126, v126 quad_perm:[2,3,0,1] row_mask:0xf bank_mask:0xf bound_ctrl:1
	s_cmp_lt_i32 s98, s4
	v_mul_f32_e32 v132, v130, v130
	v_sub_f32_e32 v133, v129, v131
	s_cselect_b64 s[88:89], -1, 0
	v_cndmask_b32_e64 v134, 0, 0.5, s[88:89]
	v_lshlrev_b32_e32 v135, 16, v46
	v_add_f32_dpp v126, v126, v126 row_half_mirror row_mask:0xf bank_mask:0xf bound_ctrl:1
	v_mov_b32_dpp v132, v132 quad_perm:[1,0,3,2] row_mask:0xf bank_mask:0xf bound_ctrl:1
	v_fmac_f32_e32 v131, v18, v133
	v_cndmask_b32_e64 v136, 0, 0.5, s[84:85]
	v_lshlrev_b32_e32 v137, 16, v42
	v_mul_f32_e32 v135, v134, v135
	v_mul_f32_e32 v138, v20, v131
	v_add_f32_dpp v126, v126, v126 row_mirror row_mask:0xf bank_mask:0xf bound_ctrl:1
	v_fmac_f32_e32 v132, v130, v130
	v_lshlrev_b32_e32 v139, 16, v54
	v_fmac_f32_e32 v135, v136, v137
	v_mul_f32_e32 v140, v138, v138
	v_add_f32_dpp v132, v132, v132 quad_perm:[2,3,0,1] row_mask:0xf bank_mask:0xf bound_ctrl:1
	v_sub_f32_e32 v141, v135, v139
	v_readlane_b32 s36, v126, 48
	v_mov_b32_dpp v140, v140 quad_perm:[1,0,3,2] row_mask:0xf bank_mask:0xf bound_ctrl:1
	v_fmac_f32_e32 v139, v18, v141
	v_readlane_b32 s3, v126, 16
	v_readlane_b32 s10, v126, 32
	v_add_f32_dpp v132, v132, v132 row_half_mirror row_mask:0xf bank_mask:0xf bound_ctrl:1
	v_fmac_f32_e32 v140, v138, v138
	v_mul_f32_e32 v142, v20, v139
	v_readlane_b32 s1, v126, 0
	v_mov_b32_e32 v143, s36
	v_add_f32_dpp v132, v132, v132 row_mirror row_mask:0xf bank_mask:0xf bound_ctrl:1
	v_add_f32_dpp v140, v140, v140 quad_perm:[2,3,0,1] row_mask:0xf bank_mask:0xf bound_ctrl:1
	v_mul_f32_e32 v144, v142, v142
	v_mov_b32_e32 v145, s3
	v_add_f32_e32 v143, s10, v143
	v_add_f32_e32 v145, s1, v145
	v_mov_b32_dpp v144, v144 quad_perm:[1,0,3,2] row_mask:0xf bank_mask:0xf bound_ctrl:1
	v_add_u32_e32 v146, s7, v28
	v_readlane_b32 s3, v132, 16
	v_readlane_b32 s10, v132, 48
	v_add_f32_dpp v140, v140, v140 row_half_mirror row_mask:0xf bank_mask:0xf bound_ctrl:1
	v_add_f32_e32 v145, v145, v143
	v_readlane_b32 s1, v132, 0
	v_readlane_b32 s7, v132, 32
	v_fmac_f32_e32 v144, v142, v142
	v_lshlrev_b32_e32 v72, 16, v72
	v_lshlrev_b32_e32 v39, 16, v39
	v_add_f32_dpp v140, v140, v140 row_mirror row_mask:0xf bank_mask:0xf bound_ctrl:1
	v_max_f32_e32 v145, 0x179abe15, v145
	v_mov_b32_e32 v147, s3
	v_mov_b32_e32 v148, s10
	v_add_f32_dpp v144, v144, v144 quad_perm:[2,3,0,1] row_mask:0xf bank_mask:0xf bound_ctrl:1
	v_lshlrev_b32_e32 v69, 16, v69
	v_mul_f32_e32 v72, v120, v72
	v_add_f32_e32 v39, v73, v39
	v_rsq_f32_e32 v145, v145
	v_add_f32_e32 v147, s1, v147
	v_add_f32_e32 v148, s7, v148
	v_readlane_b32 s3, v140, 16
	v_readlane_b32 s10, v140, 48
	v_lshlrev_b32_e32 v71, 16, v71
	v_fmac_f32_e32 v72, v119, v69
	v_mul_f32_e32 v149, 0x3fb8aa3b, v39
	v_lshlrev_b32_e32 v51, 16, v51
	v_add_f32_dpp v144, v144, v144 row_half_mirror row_mask:0xf bank_mask:0xf bound_ctrl:1
	v_mul_f32_e32 v150, 0xbfb8aa3b, v39
	v_readlane_b32 s1, v140, 0
	v_readlane_b32 s7, v140, 32
	v_sub_f32_e32 v151, v72, v71
	v_exp_f32_e32 v149, v149
	v_add_f32_e32 v152, -1.0, v51
	v_add_f32_e32 v147, v147, v148
	v_lshlrev_b32_e32 v65, 16, v65
	v_mul_f32_e32 v153, v124, v145
	v_exp_f32_e32 v150, v150
	v_lshlrev_b32_e32 v62, 16, v62
	v_lshlrev_b32_e32 v27, 16, v27
; __device__ __forceinline__ float bf2f(unsigned v) { return __uint_as_float(v << 16); }
; __device__ __forceinline__ bf16_t f2bf(float f) { return (bf16_t)(pkbf(f, 0.f) & 0xffffu); }
; __device__ __forceinline__ void scan_unit_mfma(const TI ti, CArgs& a, int l, int u, bool ctx_out, unsigned char* ldsg) {
;     ...
; #pragma unroll
;                     for (int x = 0; x < 11; ++x) cur[i4][x] = nxt[i4][x];
;     ...
;                 for (int i4 = 0; i4 < 4; ++i4) {
;                     const int t = 4 * (k & 3) + i4; const int tok = SC2_TOK(Tn_, cc_, t);
;                     Lsum = (t == 0) ? 0.f : Lsum; ePprev = (t == 0) ? 1.f : ePprev;
;                     const float mp_ = tok > 0 ? 0.5f : 0.f, mn_ = tok < Tn_ - 1 ? 0.5f : 0.f;
;                     const float xr = bf2f(cur[i4][1]), xk = bf2f(cur[i4][4]), xv = bf2f(cur[i4][7]);
;                     const float zr = xr + mur * ((mp_ * bf2f(cur[i4][0]) + mn_ * bf2f(cur[i4][2])) - xr);
;                     const float zk = xk + muk * ((mp_ * bf2f(cur[i4][3]) + mn_ * bf2f(cur[i4][5])) - xk);
;                     const float zv = xv + muv * ((mp_ * bf2f(cur[i4][6]) + mn_ * bf2f(cur[i4][8])) - xv);
;                     const float kkv = zk * kkg; const float ssq = wave_sum(kkv * kkv); const float kkn = kkv * rsqrtf(fmaxf(ssq, 1e-24f));
;                     const float ad = bf2f(cur[i4][10]); const float kd = zk * (1.f + (ad - 1.f) * kag);
;                     Lsum += bf2f(cur[i4][9]);
;                     const float eP = __expf(Lsum), eI = __expf(-Lsum);
;                     AR[t * 72 + lane] = f2bf(-kkn * ePprev); AR[(16 + t) * 72 + lane] = f2bf(zr * eP);
;                     const bf16_t bt = f2bf(kkn * ad * eI), kt = f2bf(kd * eI);
;                     BK[t * 72 + lane] = bt; BK[(16 + t) * 72 + lane] = kt;
;                     BKT[lane * 40 + t] = bt; BKT[lane * 40 + 16 + t] = kt;
;                     VTT[lane * 24 + t] = f2bf(zv);
;                     PC[lane] = eP;
;                     ePprev = eP;
;                 }
	v_mov_b32_e32 v154, s3
	v_mov_b32_e32 v155, s10
	v_add_f32_dpp v144, v144, v144 row_mirror row_mask:0xf bank_mask:0xf bound_ctrl:1
	v_fmac_f32_e32 v71, v0, v151
	v_fma_f32 v152, v21, v152, 1.0
	v_max_f32_e32 v147, 0x179abe15, v147
	v_lshlrev_b32_e32 v56, 16, v56
	v_mul_f32_e32 v65, v120, v65
	v_mul_f32_e64 v156, v74, -v153
	v_mul_f32_e32 v51, v153, v51
	v_lshlrev_b32_e32 v52, 16, v52
	v_mul_f32_e32 v62, v122, v62
	v_add_f32_e32 v27, v39, v27
	v_add_f32_e32 v154, s1, v154
	v_add_f32_e32 v155, s7, v155
	v_mul_f32_e32 v152, v152, v70
	v_mul_f32_e32 v157, v149, v71
	v_rsq_f32_e32 v147, v147
	v_readlane_b32 s3, v144, 16
	v_readlane_b32 s5, v144, 48
	v_lshlrev_b32_e32 v68, 16, v68
	v_fmac_f32_e32 v65, v119, v56
	v_cvt_pk_bf16_f32 v156, v156, s0
	v_mul_f32_e32 v51, v150, v51
	v_lshlrev_b32_e32 v64, 16, v64
	v_fmac_f32_e32 v62, v121, v52
	v_mul_f32_e32 v158, 0x3fb8aa3b, v27
	v_lshlrev_b32_e32 v34, 16, v34
	v_add_f32_e32 v154, v154, v155
	v_mul_f32_e32 v159, v150, v152
	v_cvt_pk_bf16_f32 v157, v157, s0
	v_mul_f32_e32 v160, 0xbfb8aa3b, v27
	v_readlane_b32 s1, v144, 0
	v_readlane_b32 s4, v144, 32
	v_sub_f32_e32 v161, v65, v68
	ds_write_b16 v146, v156
	v_cvt_pk_bf16_f32 v51, v51, s0
	v_sub_f32_e32 v162, v62, v64
	v_exp_f32_e32 v158, v158
	v_add_f32_e32 v163, -1.0, v34
	v_max_f32_e32 v154, 0x179abe15, v154
	v_cvt_pk_bf16_f32 v159, v159, s0
	ds_write_b16 v146, v157 offset:2304
	v_lshlrev_b32_e32 v40, 16, v40
	v_mul_f32_e32 v164, v130, v147
	v_exp_f32_e32 v160, v160
	v_lshlrev_b32_e32 v165, 16, v59
	v_lshlrev_b32_e32 v166, 16, v41
	v_mov_b32_e32 v167, s3
	v_mov_b32_e32 v168, s5
	v_fmac_f32_e32 v68, v19, v161
	v_add_u32_e32 v169, s33, v31
	ds_write_b16 v146, v51 offset:4608
	v_fmac_f32_e32 v64, v0, v162
	v_fma_f32 v163, v21, v163, 1.0
	v_rsq_f32_e32 v154, v154
	ds_write_b16 v146, v159 offset:6912
	v_lshlrev_b32_e32 v35, 16, v35
	v_mul_f32_e32 v40, v122, v40
	v_mul_f32_e64 v170, v149, -v164
	v_mul_f32_e32 v34, v164, v34
	v_lshlrev_b32_e32 v30, 16, v30
	v_mul_f32_e32 v165, v127, v165
	v_add_f32_e32 v27, v27, v166
	v_add_f32_e32 v167, s1, v167
	v_add_f32_e32 v168, s4, v168
	ds_write_b16 v169, v51
	v_cvt_pk_bf16_f32 v171, v68, s0
	v_add_u32_e32 v174, s33, v29
	v_mul_f32_e32 v163, v163, v61
	v_mul_f32_e32 v175, v158, v64
	ds_write_b16 v169, v159 offset:32
	v_lshlrev_b32_e32 v55, 16, v55
	v_fmac_f32_e32 v40, v121, v35
	v_cvt_pk_bf16_f32 v170, v170, s0
	v_mul_f32_e32 v34, v160, v34
	v_lshlrev_b32_e32 v176, 16, v63
	v_fmac_f32_e32 v165, v125, v30
	v_mul_f32_e32 v177, 0x3fb8aa3b, v27
	v_lshlrev_b32_e32 v179, 16, v49
	v_add_f32_e32 v167, v167, v168
	ds_write_b16 v174, v171
	v_cvt_pk_bf16_f32 v175, v175, s0
	v_mul_f32_e32 v182, v160, v163
	v_mul_f32_e32 v183, v138, v154
	v_mul_f32_e32 v184, 0xbfb8aa3b, v27
	v_sub_f32_e32 v185, v40, v55
	ds_write_b16 v146, v170 offset:144
	v_cvt_pk_bf16_f32 v34, v34, s0
	v_sub_f32_e32 v197, v165, v176
	v_exp_f32_e32 v177, v177
	v_add_f32_e32 v198, -1.0, v179
	v_max_f32_e32 v167, 0x179abe15, v167
	ds_write_b16 v146, v175 offset:2448
	v_cvt_pk_bf16_f32 v182, v182, s0
	v_lshlrev_b32_e32 v199, 16, v37
	v_exp_f32_e32 v184, v184
	v_mul_f32_e64 v200, v158, -v183
	v_lshlrev_b32_e32 v201, 16, v60
	v_lshlrev_b32_e32 v26, 16, v26
	v_fmac_f32_e32 v55, v19, v185
	ds_write_b16 v146, v34 offset:4752
	v_fmac_f32_e32 v176, v0, v197
	v_fma_f32 v198, v21, v198, 1.0
	v_rsq_f32_e32 v167, v167
	ds_write_b16 v146, v182 offset:7056
	v_mul_f32_e32 v199, v127, v199
	v_lshlrev_b32_e32 v23, 16, v23
	v_mul_f32_e32 v183, v183, v179
	v_lshlrev_b32_e32 v202, 16, v50
	v_mul_f32_e32 v201, v134, v201
	v_add_f32_e32 v73, v27, v26
	ds_write_b16 v169, v34 offset:2
	v_cvt_pk_bf16_f32 v203, v55, s0
	v_mul_f32_e32 v198, v198, v131
	v_mul_f32_e32 v204, v177, v176
	ds_write_b16 v169, v182 offset:34
	v_lshlrev_b32_e32 v205, 16, v53
	v_fmac_f32_e32 v199, v125, v23
	v_cvt_pk_bf16_f32 v200, v200, s0
	v_mul_f32_e32 v183, v184, v183
	v_lshlrev_b32_e32 v206, 16, v58
	v_fmac_f32_e32 v201, v136, v202
	v_mul_f32_e32 v207, 0x3fb8aa3b, v73
	v_lshlrev_b32_e32 v208, 16, v43
	ds_write_b16 v174, v203 offset:2
	v_mul_f32_e32 v209, v184, v198
	v_cvt_pk_bf16_f32 v204, v204, s0
	v_mul_f32_e32 v210, 0xbfb8aa3b, v73
	v_mul_f32_e32 v211, v142, v167
	v_sub_f32_e32 v212, v199, v205
	ds_write_b16 v146, v200 offset:288
	v_cvt_pk_bf16_f32 v183, v183, s0
	v_sub_f32_e32 v213, v201, v206
	v_exp_f32_e32 v74, v207
	v_add_f32_e32 v214, -1.0, v208
	v_cvt_pk_bf16_f32 v209, v209, s0
	ds_write_b16 v146, v204 offset:2592
	v_lshlrev_b32_e32 v38, 16, v38
	v_exp_f32_e32 v210, v210
	v_mul_f32_e64 v215, v177, -v211
	v_fmac_f32_e32 v205, v19, v212
	ds_write_b16 v146, v183 offset:4896
	v_fmac_f32_e32 v206, v0, v213
	v_fma_f32 v214, v21, v214, 1.0
	ds_write_b16 v146, v209 offset:7200
	v_mul_f32_e32 v134, v134, v38
	v_lshlrev_b32_e32 v32, 16, v32
	v_mul_f32_e32 v211, v211, v208
	ds_write_b16 v169, v183 offset:4
	v_cvt_pk_bf16_f32 v216, v205, s0
	v_mul_f32_e32 v214, v214, v139
	v_mul_f32_e32 v217, v74, v206
	ds_write_b16 v169, v209 offset:36
	v_lshlrev_b32_e32 v218, 16, v48
	v_fmac_f32_e32 v134, v136, v32
	v_cvt_pk_bf16_f32 v215, v215, s0
	v_mul_f32_e32 v211, v210, v211
	ds_write_b16 v174, v216 offset:4
	v_cvt_pk_bf16_f32 v217, v217, s0
	v_mul_f32_e32 v219, v210, v214
	v_sub_f32_e32 v220, v134, v218
	ds_write_b16 v146, v215 offset:432
	v_cvt_pk_bf16_f32 v211, v211, s0
	ds_write_b16 v146, v217 offset:2736
	v_cvt_pk_bf16_f32 v219, v219, s0
	v_fmac_f32_e32 v218, v19, v220
	ds_write_b16 v146, v211 offset:5040
	ds_write_b16 v146, v219 offset:7344
	ds_write_b16 v169, v211 offset:6
	v_cvt_pk_bf16_f32 v221, v218, s0
	ds_write_b16 v169, v219 offset:38
	ds_write_b16 v174, v221 offset:6
	ds_write_b32 v36, v74 offset:17408
	s_waitcnt vmcnt(0)
	v_mov_b32_e32 v43, v118
	v_mov_b32_e32 v26, v117
	v_mov_b32_e32 v38, v116
	v_mov_b32_e32 v48, v114
	v_mov_b32_e32 v32, v113
	v_mov_b32_e32 v46, v115
	v_mov_b32_e32 v54, v111
	v_mov_b32_e32 v42, v110
	v_mov_b32_e32 v60, v112
	v_mov_b32_e32 v58, v109
	v_mov_b32_e32 v50, v108
	v_mov_b32_e32 v49, v107
	v_mov_b32_e32 v41, v106
	v_mov_b32_e32 v37, v105
	v_mov_b32_e32 v53, v104
	v_mov_b32_e32 v23, v99
	v_mov_b32_e32 v45, v103
	v_mov_b32_e32 v57, v102
	v_mov_b32_e32 v25, v98
	v_mov_b32_e32 v59, v101
	v_mov_b32_e32 v63, v100
	v_mov_b32_e32 v30, v83
	v_mov_b32_e32 v34, v82
	v_mov_b32_e32 v27, v79
	v_mov_b32_e32 v40, v78
	v_mov_b32_e32 v55, v77
	v_mov_b32_e32 v35, v17
	v_mov_b32_e32 v47, v76
	v_mov_b32_e32 v61, v75
	v_mov_b32_e32 v44, v14
	v_mov_b32_e32 v62, v16
	v_mov_b32_e32 v64, v15
	v_mov_b32_e32 v52, v13
	v_mov_b32_e32 v51, v12
	v_mov_b32_e32 v39, v11
	v_mov_b32_e32 v65, v10
	v_mov_b32_e32 v68, v8
	v_mov_b32_e32 v56, v7
	v_mov_b32_e32 v67, v9
	v_mov_b32_e32 v70, v5
	v_mov_b32_e32 v66, v4
	v_mov_b32_e32 v72, v6
	v_mov_b32_e32 v71, v3
	v_mov_b32_e32 v69, v2
